# MLA loop: defer-max fast path keeps running max and its log2 offset in registers, alpha and new max only computed on the rare rescale path
# speedup vs baseline: 1.0884x; 1.0022x over previous
; #define ISSUE_K(j) do { const int _t = (j) < NT ? (j) : NT - 1; char* _d = K_lds + ((j) & 3) * SHM_K8; if (wid < 6) GLDS(K8 + (size_t)_t * 6144 + t16u, _d + tid16); \
;     if (wid < 3) GLDS(Kp8 + (size_t)_t * 3072 + t16u, _d + 6144 + tid16); } while (0)
; #define ISSUE_V(j) do { const int _t = (j) < NT ? (j) : NT - 1; GLDS(V8 + (size_t)_t * 8192 + t16u, V_lds + ((j) & 3) * SHM_V8 + tid16); } while (0)
; #define TILE_SYNC() do { asm volatile("s_waitcnt vmcnt(0)" ::: "memory"); __syncthreads(); } while (0)
; DEVINL void mla_block(const Params& p, const bf16_t* __restrict__ Qn, const bf16_t* __restrict__ Qr, const char* __restrict__ K8, const char* __restrict__ Kp8,
;                       const char* __restrict__ V8, const bf16_t* __restrict__ Gb, bf16_t* __restrict__ Yb, char* lds, int pos0) {
;     ...
;   ISSUE_K(0); ISSUE_K(1); ISSUE_K(2); ISSUE_V(0); ISSUE_V(1); TILE_SYNC();
.LBB0_559:
	s_or_b64 exec, exec, s[8:9]
	s_mul_i32 s8, s75, 0x208000
	s_add_u32 s14, s58, s8
	v_add_u32_e32 v0, 0x9000, v172
	s_addc_u32 s15, s59, 0
	v_readfirstlane_b32 s9, v0
	v_add_u32_e32 v2, 0xb000, v172
	v_lshl_add_u64 v[140:141], s[14:15], 0, v[138:139]
	s_mov_b32 m0, s9
	v_readfirstlane_b32 s9, v2
	global_load_lds_dwordx4 v[140:141], off
	v_lshl_add_u64 v[0:1], v[140:141], 0, s[48:49]
	s_mov_b32 m0, s9
	v_lshlrev_b32_e32 v170, 9, v48
	global_load_lds_dwordx4 v[0:1], off
	v_and_b32_e32 v0, 0x3fffffc0, v166
	v_lshl_add_u32 v171, v0, 2, s68
	v_add_u32_e32 v0, 0, v170
	v_lshlrev_b32_e32 v176, 3, v167
	v_lshlrev_b32_e32 v175, 4, v167
	v_add_u32_e32 v49, v0, v176
	v_add3_u32 v173, v0, v170, v175
	v_add_u32_e32 v0, 0x1000, v49
	s_waitcnt vmcnt(0)
	s_waitcnt vmcnt(0) lgkmcnt(0)
	s_barrier
; DEVINL int crow(int r, int hi) { return (r & 3) + 8 * (r >> 2) + 4 * hi; }
; #define ISSUE_K(j) do { const int _t = (j) < NT ? (j) : NT - 1; char* _d = K_lds + ((j) & 3) * SHM_K8; if (wid < 6) GLDS(K8 + (size_t)_t * 6144 + t16u, _d + tid16); \
;     if (wid < 3) GLDS(Kp8 + (size_t)_t * 3072 + t16u, _d + 6144 + tid16); } while (0)
; #define ISSUE_V(j) do { const int _t = (j) < NT ? (j) : NT - 1; GLDS(V8 + (size_t)_t * 8192 + t16u, V_lds + ((j) & 3) * SHM_V8 + tid16); } while (0)
; DEVINL void partialSM(f32x16& p0, f32x16& p1, float& m_reg, float& mn, float& alpha, int kvalid, int hi) {
;   constexpr float C = MLA_SCALE * 1.4426950408889634f;
;   if (kvalid < 64) {
; #pragma unroll
;     for (int r = 0; r < 16; ++r) { if (crow(r, hi) >= kvalid) p0[r] = -1e30f; if (32 + crow(r, hi) >= kvalid) p1[r] = -1e30f; }
;   }
;   float pmax = p0[0];
; #pragma unroll
;   for (int r = 1; r < 16; ++r) pmax = fmaxf(pmax, p0[r]);
; #pragma unroll
;   for (int r = 0; r < 16; ++r) pmax = fmaxf(pmax, p1[r]);
;   { auto rr = __builtin_amdgcn_permlane32_swap(__float_as_uint(pmax), __float_as_uint(pmax), false, false);
;     pmax = fmaxf(__uint_as_float(rr[0]), __uint_as_float(rr[1])); }
;   if (__builtin_expect(__all(pmax - m_reg <= THR / MLA_SCALE), 1)) { mn = m_reg; alpha = 1.f; }
;   else { mn = fmaxf(m_reg, pmax); alpha = __builtin_amdgcn_exp2f((m_reg - mn) * C); m_reg = mn; }
;   const float mnC = PSHIFT - mn * C;
;   const f32x2 C2 = {C, C}, M2 = {mnC, mnC};
; #pragma unroll
;   for (int r = 0; r < 16; r += 2) { f32x2 v = {p0[r], p0[r + 1]}; v = __builtin_elementwise_fma(v, C2, M2); p0[r] = v[0]; p0[r + 1] = v[1]; }
; #pragma unroll
;   for (int r = 0; r < 16; r += 2) { f32x2 v = {p1[r], p1[r + 1]}; v = __builtin_elementwise_fma(v, C2, M2); p1[r] = v[0]; p1[r + 1] = v[1]; }
; #pragma unroll
;   for (int r = 0; r < 16; ++r) p0[r] = __builtin_amdgcn_exp2f(p0[r]);
; DEVINL void mla_block(const Params& p, const bf16_t* __restrict__ Qn, const bf16_t* __restrict__ Qr, const char* __restrict__ K8, const char* __restrict__ Kp8,
;                       const char* __restrict__ V8, const bf16_t* __restrict__ Gb, bf16_t* __restrict__ Yb, char* lds, int pos0) {
;     ...
;   ISSUE_K(0); ISSUE_K(1); ISSUE_K(2); ISSUE_V(0); ISSUE_V(1); TILE_SYNC();
;   qkt<false>(pA0, pA1, KS(0), q8, r32, hi, pA1); partialSM(pA0, pA1, m_reg, mnA, alA, 64, hi);
	ds_read2_b64 v[4:7], v0 offset1:32
	ds_read_b128 v[50:53], v173 offset:2048
	ds_read_b128 v[56:59], v173 offset:2560
	ds_read2_b64 v[60:63], v0 offset0:128 offset1:160
	ds_read_b128 v[16:19], v173 offset:512
	ds_read_b128 v[0:3], v173
	s_waitcnt lgkmcnt(5)
	v_mov_b32_e32 v20, v6
	v_mov_b32_e32 v21, v7
	s_waitcnt lgkmcnt(0)
	v_mfma_scale_f32_32x32x64_f8f6f4 v[32:47], v[0:5], v[120:125], 0, v162, v162 op_sel_hi:[0,0,0] cbsz:2 blgp:2
	s_mov_b32 s12, s13
	s_mov_b32 s14, s13
	s_mov_b32 s15, s13
	s_mov_b32 s16, s13
	s_mov_b32 s17, s13
	s_mov_b32 s18, s13
	s_mov_b32 s19, s13
	v_mfma_scale_f32_32x32x64_f8f6f4 v[16:31], v[16:21], v[120:125], 0, v162, v162 op_sel_hi:[0,0,0] cbsz:2 blgp:2
	s_mov_b32 s20, s13
	s_mov_b32 s21, s13
	s_mov_b32 s22, s13
	s_mov_b32 s23, s13
	s_mov_b32 s24, s13
	s_mov_b32 s25, s13
	s_mov_b32 s26, s13
	s_mov_b32 s27, s13
	v_mov_b64_e32 v[0:1], s[12:13]
	v_and_b32_e32 v169, 63, v166
	v_lshlrev_b32_e32 v174, 10, v48
	s_mov_b32 s53, 4
	v_mov_b64_e32 v[2:3], s[14:15]
	v_mov_b64_e32 v[4:5], s[16:17]
	v_mov_b64_e32 v[6:7], s[18:19]
	v_mov_b64_e32 v[8:9], s[20:21]
	v_mov_b64_e32 v[10:11], s[22:23]
	v_mov_b64_e32 v[12:13], s[24:25]
	v_mov_b64_e32 v[14:15], s[26:27]
	v_mov_b32_e32 v54, v60
	v_mov_b32_e32 v55, v61
	v_mov_b32_e32 v60, v62
	v_mov_b32_e32 v61, v63
	v_add_u32_e32 v49, 0x2000, v49
	v_mfma_scale_f32_32x32x64_f8f6f4 v[32:47], v[50:55], v[126:131], v[32:47], v162, v162 op_sel_hi:[0,0,0] cbsz:2 blgp:2
	ds_read_b128 v[50:53], v173 offset:6144
	ds_read_b128 v[62:65], v173 offset:6656
	ds_read2_b64 v[66:69], v49 offset1:32
	v_mfma_scale_f32_32x32x64_f8f6f4 v[16:31], v[56:61], v[126:131], v[16:31], v162, v162 op_sel_hi:[0,0,0] cbsz:2 blgp:2
	s_waitcnt lgkmcnt(0)
	v_mov_b32_e32 v54, v66
	v_mov_b32_e32 v55, v67
	v_mov_b32_e32 v66, v68
	v_mov_b32_e32 v67, v69
	v_mfma_scale_f32_32x32x64_f8f6f4 v[32:47], v[50:55], v[132:137], v[32:47], v162, v162 op_sel_hi:[0,0,0] cbsz:2 blgp:2
	s_nop 0
	v_mfma_scale_f32_32x32x64_f8f6f4 v[16:31], v[62:67], v[132:137], v[16:31], v162, v162 op_sel_hi:[0,0,0] cbsz:2 blgp:2
	s_nop 9
	v_max_f32_e32 v49, v33, v33
	v_max_f32_e32 v50, v32, v32
	v_max_f32_e32 v49, v50, v49
	v_max3_f32 v49, v49, v34, v35
	v_max3_f32 v49, v49, v36, v37
	v_max3_f32 v49, v49, v38, v39
	v_max3_f32 v49, v49, v40, v41
	v_max3_f32 v49, v49, v42, v43
	v_max3_f32 v49, v49, v44, v45
	v_max3_f32 v49, v49, v46, v47
	v_max3_f32 v49, v49, v16, v17
	v_max3_f32 v49, v49, v18, v19
	v_max3_f32 v49, v49, v20, v21
	v_max3_f32 v49, v49, v22, v23
	v_max3_f32 v49, v49, v24, v25
	v_max3_f32 v49, v49, v26, v27
	v_max3_f32 v49, v49, v28, v29
	v_max3_f32 v49, v49, v30, v31
	v_mov_b32_e32 v50, v49
	s_nop 1
	v_permlane32_swap_b32_e32 v49, v50
	v_max_f32_e32 v50, v50, v50
	v_max_f32_e32 v49, v49, v49
	v_max_f32_e32 v49, v49, v50
	v_add_f32_e32 v50, 0x7149f2ca, v49
	v_max_f32_e32 v49, 0xf149f2ca, v49
	v_sub_f32_e32 v51, 0xf149f2ca, v49
	v_mul_f32_e32 v51, 0x3dd53b94, v51
	v_cmp_ge_f32_e32 vcc, s69, v50
	v_exp_f32_e32 v51, v51
	s_cmp_eq_u64 vcc, exec
	s_cselect_b64 vcc, -1, 0
	v_cndmask_b32_e32 v181, v49, v163, vcc
	v_fmamk_f32 v50, v181, 0xbdd53b94, v164
	v_pk_fma_f32 v[32:33], v[32:33], s[50:51], v[50:51] op_sel_hi:[1,0,0]
	v_pk_fma_f32 v[34:35], v[34:35], s[50:51], v[50:51] op_sel_hi:[1,0,0]
	v_pk_fma_f32 v[36:37], v[36:37], s[50:51], v[50:51] op_sel_hi:[1,0,0]
	v_pk_fma_f32 v[38:39], v[38:39], s[50:51], v[50:51] op_sel_hi:[1,0,0]
	v_pk_fma_f32 v[40:41], v[40:41], s[50:51], v[50:51] op_sel_hi:[1,0,0]
	v_pk_fma_f32 v[42:43], v[42:43], s[50:51], v[50:51] op_sel_hi:[1,0,0]
	v_pk_fma_f32 v[44:45], v[44:45], s[50:51], v[50:51] op_sel_hi:[1,0,0]
	v_pk_fma_f32 v[46:47], v[46:47], s[50:51], v[50:51] op_sel_hi:[1,0,0]
	v_exp_f32_e32 v65, v32
	v_exp_f32_e32 v197, v33
	v_exp_f32_e32 v187, v34
	v_exp_f32_e32 v189, v35
	v_exp_f32_e32 v195, v36
	v_exp_f32_e32 v196, v37
	v_exp_f32_e32 v191, v38
	v_exp_f32_e32 v192, v39
	v_exp_f32_e32 v193, v40
	v_exp_f32_e32 v194, v41
	v_exp_f32_e32 v183, v42
	v_exp_f32_e32 v184, v43
	v_exp_f32_e32 v188, v44
	v_exp_f32_e32 v190, v45
	v_exp_f32_e32 v185, v46
	v_exp_f32_e32 v186, v47
	s_add_u32 s8, s30, s8
	v_cndmask_b32_e64 v179, v51, 1.0, vcc
	v_pk_fma_f32 v[148:149], v[30:31], s[50:51], v[50:51] op_sel_hi:[1,0,0]
	v_pk_fma_f32 v[150:151], v[28:29], s[50:51], v[50:51] op_sel_hi:[1,0,0]
	v_pk_fma_f32 v[152:153], v[26:27], s[50:51], v[50:51] op_sel_hi:[1,0,0]
	v_pk_fma_f32 v[154:155], v[24:25], s[50:51], v[50:51] op_sel_hi:[1,0,0]
	v_pk_fma_f32 v[156:157], v[22:23], s[50:51], v[50:51] op_sel_hi:[1,0,0]
	v_pk_fma_f32 v[82:83], v[20:21], s[50:51], v[50:51] op_sel_hi:[1,0,0]
	v_pk_fma_f32 v[158:159], v[18:19], s[50:51], v[50:51] op_sel_hi:[1,0,0]
	v_pk_fma_f32 v[160:161], v[16:17], s[50:51], v[50:51] op_sel_hi:[1,0,0]
	v_lshlrev_b32_e32 v177, 4, v48
	s_addc_u32 s9, s31, 0
	v_mov_b64_e32 v[62:63], v[14:15]
	v_mov_b64_e32 v[30:31], v[14:15]
	v_mov_b64_e32 v[46:47], v[14:15]
	v_lshl_add_u64 v[142:143], s[6:7], 0, v[138:139]
	v_lshl_add_u64 v[144:145], s[34:35], 0, v[138:139]
	v_cmp_gt_u32_e64 s[6:7], 32, v169
	v_lshl_add_u32 v178, v167, 2, v171
	v_lshl_add_u64 v[146:147], s[8:9], 0, v[138:139]
	v_mov_b32_e32 v180, 0
	s_mov_b64 s[14:15], 0x89dc400
	v_mov_b64_e32 v[60:61], v[12:13]
	v_mov_b64_e32 v[58:59], v[10:11]
	v_mov_b64_e32 v[56:57], v[8:9]
	v_mov_b64_e32 v[54:55], v[6:7]
	v_mov_b64_e32 v[52:53], v[4:5]
	v_mov_b64_e32 v[50:51], v[2:3]
	v_mov_b64_e32 v[48:49], v[0:1]
	v_mov_b64_e32 v[28:29], v[12:13]
	v_mov_b64_e32 v[26:27], v[10:11]
	v_mov_b64_e32 v[24:25], v[8:9]
	v_mov_b64_e32 v[22:23], v[6:7]
	v_mov_b64_e32 v[20:21], v[4:5]
	v_mov_b64_e32 v[18:19], v[2:3]
	v_mov_b64_e32 v[16:17], v[0:1]
	v_mov_b64_e32 v[44:45], v[12:13]
	v_mov_b64_e32 v[42:43], v[10:11]
	v_mov_b64_e32 v[40:41], v[8:9]
	v_mov_b64_e32 v[38:39], v[6:7]
	v_mov_b64_e32 v[36:37], v[4:5]
	v_mov_b64_e32 v[34:35], v[2:3]
	v_mov_b64_e32 v[32:33], v[0:1]
	v_mov_b32_e32 v232, v112
	v_mov_b32_e32 v233, v112
	v_mov_b32_e32 v234, v112
	v_mov_b32_e32 v235, v112
	v_mov_b32_e32 v236, v112
	v_mov_b32_e32 v237, v112
	v_mov_b32_e32 v238, v112
	v_mov_b32_e32 v239, v112
	v_add_u32_e32 v176, v170, v176
	v_add_u32_e32 v176, 0x1000, v176
	v_add_u32_e32 v174, 0x2400, v173
	v_add_u32_e32 v175, 0x2400, v176
	ds_read_b128 v[204:207], v174
	ds_read_b64 v[208:209], v175
	ds_read_b128 v[216:219], v174 offset:512
	ds_read_b64 v[220:221], v175 offset:256
	s_lshl_b32 s78, s3, 4
	s_add_i32 s79, s78, 0x9000
	s_mul_i32 s80, s75, 0x186000
	s_add_u32 s80, s56, s80
	s_addc_u32 s81, s57, 0
	s_mov_b64 s[82:83], s[34:35]
	s_mul_i32 s84, s75, 0x208000
	s_add_u32 s84, s58, s84
	s_addc_u32 s85, s59, 0
	v_lshlrev_b32_e32 v231, 4, v169
	v_mov_b32_e32 v227, v181
	v_fmamk_f32 v230, v181, 0xbdd53b94, v164
	s_cmp_ge_u32 s3, 0x100
	s_cbranch_scc0 .Lprio_skip
	s_setprio 2

; template <bool FUSE>
; DEVINL void qkt(f32x16& p0, f32x16& p1, const char* Ks, const i32x8* q8, int r32, int hi, f32x16& e1) {
;   p0 = f32x16{}; p1 = f32x16{};
;   const char* ka = Ks + hi * 1024 + r32 * 16; const char* kb = Ks + 4096 + hi * 512 + r32 * 8;
;   const char* ra = Ks + 6144 + hi * 1024 + r32 * 16; const char* rb = Ks + 6144 + 2048 + hi * 512 + r32 * 8;
;   u32x4 fa[3][2]; u32x2 fb[3][2];
;     ...
;   QK_LD(0, 0);
; #pragma unroll
;   for (int t = 0; t < 3; ++t) {
;     if (t + 1 < 3) QK_LD(t + 1, (t + 1) % 3);
;     const i32x8 a0 = mk6((int)fa[t][0][0], (int)fa[t][0][1], (int)fa[t][0][2], (int)fa[t][0][3], (int)fb[t][0][0], (int)fb[t][0][1]);
;     const i32x8 a1 = mk6((int)fa[t][1][0], (int)fa[t][1][1], (int)fa[t][1][2], (int)fa[t][1][3], (int)fb[t][1][0], (int)fb[t][1][1]);
;     p0 = MFMA6(a0, q8[t], p0);
;     if (FUSE) {
; #pragma unroll
;       for (int r = 0; r < 3; ++r) { const int rr = t * 6 + r; if (rr < 16) e1[rr] = __builtin_amdgcn_exp2f(e1[rr]); }
;     }
;     p1 = MFMA6(a1, q8[t], p1);
;     if (FUSE) {
; #pragma unroll
; DEVINL void pv_psm(f32x16* o, const VFrag& f, const i32x8& pa, f32x16& lsum, const i32x8& ones8,
;                    f32x16& p0, f32x16& p1, float& m_reg, float& mn, float& alpha, int kvalid, int hi) {
;   constexpr float C = MLA_SCALE * 1.4426950408889634f;
;     ...
;   if (kvalid < 64) {
; #pragma unroll
;     for (int r = 0; r < 16; ++r) { if (crow(r, hi) >= kvalid) p0[r] = -1e30f; if (32 + crow(r, hi) >= kvalid) p1[r] = -1e30f; }
;   }
;   PVM(0);
;   float pmax = p0[0];
; #pragma unroll
;   for (int r = 1; r < 16; ++r) pmax = fmaxf(pmax, p0[r]);
;   SBAR();
;   PVM(1);
; #pragma unroll
;   for (int r = 0; r < 16; ++r) pmax = fmaxf(pmax, p1[r]);
;   { auto rr = __builtin_amdgcn_permlane32_swap(__float_as_uint(pmax), __float_as_uint(pmax), false, false);
;     pmax = fmaxf(__uint_as_float(rr[0]), __uint_as_float(rr[1])); }
;   SBAR();
;   PVM(2);
;   if (__builtin_expect(__all(pmax - m_reg <= THR / MLA_SCALE), 1)) { mn = m_reg; alpha = 1.f; }
;   else { mn = fmaxf(m_reg, pmax); alpha = __builtin_amdgcn_exp2f((m_reg - mn) * C); m_reg = mn; }
;   const float mnC = PSHIFT - mn * C;
;   const f32x2 C2 = {C, C}, M2 = {mnC, mnC};
; #pragma unroll
;   for (int r = 0; r < 16; r += 2) { f32x2 v = {p0[r], p0[r + 1]}; v = __builtin_elementwise_fma(v, C2, M2); p0[r] = v[0]; p0[r + 1] = v[1]; }
;   SBAR();
.Ldma_done:
	s_and_b32 s12, s18, 3
	ds_read_b128 v[114:117], v174 offset:2048
	ds_read_b128 v[198:201], v174 offset:2560
	ds_read_b64 v[118:119], v175 offset:1024
	ds_read_b64 v[202:203], v175 offset:1280
	v_exp_f32_e32 v182, v82
	s_waitcnt lgkmcnt(4)
	v_exp_f32_e32 v214, v83
	v_mfma_scale_f32_32x32x64_f8f6f4 v[96:111], v[204:209], v[120:125], 0, v162, v162 op_sel_hi:[0,0,0] cbsz:2 blgp:2
	v_exp_f32_e32 v160, v160
	v_exp_f32_e32 v161, v161
	v_exp_f32_e32 v158, v158
	v_exp_f32_e32 v159, v159
	v_mfma_scale_f32_32x32x64_f8f6f4 v[80:95], v[216:221], v[120:125], 0, v162, v162 op_sel_hi:[0,0,0] cbsz:2 blgp:2
	ds_read_b128 v[66:69], v174 offset:6144
	ds_read_b128 v[72:75], v174 offset:6656
	ds_read_b64 v[70:71], v175 offset:4096
	ds_read_b64 v[76:77], v175 offset:4352
	s_waitcnt lgkmcnt(4)
	v_mfma_scale_f32_32x32x64_f8f6f4 v[96:111], v[114:119], v[126:131], v[96:111], v162, v162 op_sel_hi:[0,0,0] cbsz:2 blgp:2
	v_exp_f32_e32 v113, v156
	v_exp_f32_e32 v114, v157
	v_exp_f32_e32 v115, v154
	v_exp_f32_e32 v116, v155
	v_exp_f32_e32 v117, v152
	v_mfma_scale_f32_32x32x64_f8f6f4 v[80:95], v[198:203], v[126:131], v[80:95], v162, v162 op_sel_hi:[0,0,0] cbsz:2 blgp:2
	v_exp_f32_e32 v118, v153
	s_waitcnt lgkmcnt(0)
	v_exp_f32_e32 v119, v150
	v_mfma_scale_f32_32x32x64_f8f6f4 v[96:111], v[66:71], v[132:137], v[96:111], v162, v162 op_sel_hi:[0,0,0] cbsz:2 blgp:2
	v_exp_f32_e32 v156, v151
	v_exp_f32_e32 v157, v148
	v_exp_f32_e32 v215, v149
	v_mfma_scale_f32_32x32x64_f8f6f4 v[80:95], v[72:77], v[132:137], v[80:95], v162, v162 op_sel_hi:[0,0,0] cbsz:2 blgp:2
	s_add_i32 s8, s14, 0xf762bc00
	s_and_b32 s8, s8, 0x6000
	v_add_u32_e32 v64, s8, v173
	ds_read_b128 v[72:75], v64 offset:36864
	ds_read_b128 v[76:79], v64 offset:37376
	ds_read_b128 v[148:151], v64 offset:38912
	ds_read_b128 v[152:155], v64 offset:39424
	ds_read_b128 v[198:201], v64 offset:40960
	ds_read_b128 v[202:205], v64 offset:41472
	ds_read_b128 v[206:209], v64 offset:43008
	ds_read_b128 v[210:213], v64 offset:43520
	v_cvt_pk_fp8_f32 v64, v65, v197
	v_cvt_pk_fp8_f32 v68, v160, v161
	v_cvt_pk_fp8_f32 v65, v195, v196
	v_cvt_pk_fp8_f32 v69, v182, v214
	v_cvt_pk_fp8_f32 v66, v193, v194
	v_cvt_pk_fp8_f32 v70, v115, v116
	v_cvt_pk_fp8_f32 v67, v188, v190
	v_cvt_pk_fp8_f32 v71, v119, v156
	v_cvt_pk_fp8_f32 v64, v187, v189 op_sel:[0,0,1]
	v_cvt_pk_fp8_f32 v68, v158, v159 op_sel:[0,0,1]
	v_cvt_pk_fp8_f32 v65, v191, v192 op_sel:[0,0,1]
	v_cvt_pk_fp8_f32 v69, v113, v114 op_sel:[0,0,1]
	v_cvt_pk_fp8_f32 v66, v183, v184 op_sel:[0,0,1]
	v_cvt_pk_fp8_f32 v70, v117, v118 op_sel:[0,0,1]
	v_cvt_pk_fp8_f32 v67, v185, v186 op_sel:[0,0,1]
	v_cvt_pk_fp8_f32 v71, v157, v215 op_sel:[0,0,1]
	s_waitcnt lgkmcnt(0)
	s_nop 0
	v_mfma_scale_f32_32x32x64_f8f6f4 v[0:15], v[64:71], v[72:79], v[0:15], v162, v162 op_sel_hi:[0,0,0]
	v_max_f32_e32 v113, v96, v97
	v_max3_f32 v113, v113, v98, v99
	v_max3_f32 v113, v113, v100, v101
	v_max3_f32 v113, v113, v102, v103
	v_max3_f32 v113, v113, v104, v105
	v_max3_f32 v113, v113, v106, v107
	v_max3_f32 v113, v113, v108, v109
	v_max3_f32 v113, v113, v110, v111
	v_mfma_scale_f32_32x32x64_f8f6f4 v[48:63], v[64:71], v[148:155], v[48:63], v162, v162 op_sel_hi:[0,0,0]
	v_max3_f32 v72, v113, v80, v81
	v_max3_f32 v72, v72, v82, v83
	v_max3_f32 v72, v72, v84, v85
	v_max3_f32 v72, v72, v86, v87
	v_max3_f32 v72, v72, v88, v89
	v_max3_f32 v72, v72, v90, v91
	v_max3_f32 v72, v72, v92, v93
	v_max3_f32 v72, v72, v94, v95
	v_mov_b32_e32 v73, v72
	s_nop 1
	v_permlane32_swap_b32_e32 v72, v73
	v_max_f32_e32 v72, v72, v73
	v_mfma_scale_f32_32x32x64_f8f6f4 v[16:31], v[64:71], v[198:205], v[16:31], v162, v162 op_sel_hi:[0,0,0]
	v_sub_f32_e32 v73, v72, v227
	v_cmp_ge_f32_e32 vcc, s69, v73
	s_cmp_eq_u64 vcc, exec
	s_cselect_b64 s[8:9], -1, 0
	v_mov_b32_e32 v182, 1.0
	v_mfma_scale_f32_32x32x64_f8f6f4 v[32:47], v[64:71], v[206:213], v[32:47], v162, v162 op_sel_hi:[0,0,0]
	v_mfma_scale_f32_32x32x64_f8f6f4 v[240:255], v[232:239], v[64:71], 0, v162, v162 op_sel_hi:[0,0,0]
	s_mulk_i32 s20, 0x2400
	v_add_u32_e32 v174, s20, v173
	v_add_u32_e32 v175, s20, v176
	ds_read_b128 v[200:203], v174
	ds_read_b64 v[204:205], v175
	ds_read_b128 v[206:209], v174 offset:512
	ds_read_b64 v[210:211], v175 offset:256
	s_and_b64 vcc, exec, s[8:9]
	s_cbranch_vccnz .LBB0_572
	v_max_f32_e32 v148, v227, v72
	v_sub_f32_e32 v72, v227, v148
	v_mul_f32_e32 v72, 0x3dd53b94, v72
	v_exp_f32_e32 v182, v72
	v_mov_b32_e32 v227, v148
	v_fmamk_f32 v230, v148, 0xbdd53b94, v164
	s_and_saveexec_b64 s[16:17], s[6:7]
	ds_write_b32 v178, v182 offset:128
	s_or_b64 exec, exec, s[16:17]
	s_waitcnt lgkmcnt(0)
	v_add_u32_e32 v113, v171, v177
	ds_read_b128 v[72:75], v113 offset:224
	ds_read_b128 v[76:79], v113 offset:192
	ds_read_b128 v[114:117], v113 offset:160
	ds_read_b128 v[150:153], v113 offset:128
	s_waitcnt lgkmcnt(0)
	v_pk_mul_f32 v[12:13], v[12:13], v[72:73]
	v_pk_mul_f32 v[8:9], v[8:9], v[76:77]
	v_pk_mul_f32 v[4:5], v[4:5], v[114:115]
	v_pk_mul_f32 v[14:15], v[14:15], v[74:75]
	v_pk_mul_f32 v[10:11], v[10:11], v[78:79]
	v_pk_mul_f32 v[6:7], v[6:7], v[116:117]
	v_pk_mul_f32 v[2:3], v[2:3], v[152:153]
	v_pk_mul_f32 v[0:1], v[0:1], v[150:151]
	v_pk_mul_f32 v[60:61], v[60:61], v[72:73]
	v_pk_mul_f32 v[56:57], v[56:57], v[76:77]
	v_pk_mul_f32 v[52:53], v[52:53], v[114:115]
	v_pk_mul_f32 v[62:63], v[62:63], v[74:75]
	v_pk_mul_f32 v[58:59], v[58:59], v[78:79]
	v_pk_mul_f32 v[54:55], v[54:55], v[116:117]
	v_pk_mul_f32 v[50:51], v[50:51], v[152:153]
	v_pk_mul_f32 v[48:49], v[48:49], v[150:151]
	v_pk_mul_f32 v[28:29], v[28:29], v[72:73]
	v_pk_mul_f32 v[24:25], v[24:25], v[76:77]
	v_pk_mul_f32 v[20:21], v[20:21], v[114:115]
	v_pk_mul_f32 v[30:31], v[30:31], v[74:75]
	v_pk_mul_f32 v[26:27], v[26:27], v[78:79]
	v_pk_mul_f32 v[22:23], v[22:23], v[116:117]
	v_pk_mul_f32 v[18:19], v[18:19], v[152:153]
	v_pk_mul_f32 v[16:17], v[16:17], v[150:151]
	v_pk_mul_f32 v[44:45], v[44:45], v[72:73]
	v_pk_mul_f32 v[40:41], v[40:41], v[76:77]
	v_pk_mul_f32 v[36:37], v[36:37], v[114:115]
	v_pk_mul_f32 v[46:47], v[46:47], v[74:75]
	v_pk_mul_f32 v[42:43], v[42:43], v[78:79]
	v_pk_mul_f32 v[38:39], v[38:39], v[116:117]
	v_pk_mul_f32 v[34:35], v[34:35], v[152:153]
	v_pk_mul_f32 v[32:33], v[32:33], v[150:151]
; #define SBAR() __builtin_amdgcn_sched_barrier(0)
; DEVINL i32x8 mk6(int a, int b, int c, int d, int e, int f) { i32x8 r = __builtin_nondeterministic_value(r); r[0] = a; r[1] = b; r[2] = c; r[3] = d; r[4] = e; r[5] = f; return r; }
; #define MFMA6(A, B, C) __builtin_amdgcn_mfma_scale_f32_32x32x64_f8f6f4(A, B, C, 2, 2, 0, 0x7f7f7f7f, 0, 0x7f7f7f7f)
; #define LUPD(al) do { l_reg = l_reg * (al) + lsum[0]; } while (0)
; template <bool FUSE>
; DEVINL void qkt(f32x16& p0, f32x16& p1, const char* Ks, const i32x8* q8, int r32, int hi, f32x16& e1) {
;   p0 = f32x16{}; p1 = f32x16{};
;   const char* ka = Ks + hi * 1024 + r32 * 16; const char* kb = Ks + 4096 + hi * 512 + r32 * 8;
;   const char* ra = Ks + 6144 + hi * 1024 + r32 * 16; const char* rb = Ks + 6144 + 2048 + hi * 512 + r32 * 8;
;   u32x4 fa[3][2]; u32x2 fb[3][2];
;     ...
;   QK_LD(0, 0);
; #pragma unroll
;   for (int t = 0; t < 3; ++t) {
;     if (t + 1 < 3) QK_LD(t + 1, (t + 1) % 3);
;     const i32x8 a0 = mk6((int)fa[t][0][0], (int)fa[t][0][1], (int)fa[t][0][2], (int)fa[t][0][3], (int)fb[t][0][0], (int)fb[t][0][1]);
;     const i32x8 a1 = mk6((int)fa[t][1][0], (int)fa[t][1][1], (int)fa[t][1][2], (int)fa[t][1][3], (int)fb[t][1][0], (int)fb[t][1][1]);
;     p0 = MFMA6(a0, q8[t], p0);
;     if (FUSE) {
; #pragma unroll
;       for (int r = 0; r < 3; ++r) { const int rr = t * 6 + r; if (rr < 16) e1[rr] = __builtin_amdgcn_exp2f(e1[rr]); }
;     }
;     p1 = MFMA6(a1, q8[t], p1);
;     if (FUSE) {
; #pragma unroll
;       for (int r = 3; r < 6; ++r) { const int rr = t * 6 + r; if (rr < 16) e1[rr] = __builtin_amdgcn_exp2f(e1[rr]); }
;     }
;     SBAR();
;   }
;     ...
; }
; DEVINL void mla_block(const Params& p, const bf16_t* __restrict__ Qn, const bf16_t* __restrict__ Qr, const char* __restrict__ K8, const char* __restrict__ Kp8,
;                       const char* __restrict__ V8, const bf16_t* __restrict__ Gb, bf16_t* __restrict__ Yb, char* lds, int pos0) {
;     ...
;     qkt<true>(pA0, pA1, KS(j + 1), q8, r32, hi, pB1);
;     pv_load(vf, VS(j), r32, hi); SBAR();
;     finishSM<true>(pB0, pB1, alB, l_reg, pa); SBAR();
;     { const float alPrev = alB; pv_psm(o, vf, pa, lsum, ones8, pA0, pA1, m_reg, mnA, alA, L - (j + 1) * KVBLK, hi); LUPD(alPrev); }
.LBB0_572:
	v_pk_fma_f32 v[76:77], v[104:105], s[50:51], v[230:231] op_sel_hi:[1,0,0]
	v_pk_fma_f32 v[68:69], v[96:97], s[50:51], v[230:231] op_sel_hi:[1,0,0]
	v_exp_f32_e32 v198, v77
	v_pk_fma_f32 v[70:71], v[98:99], s[50:51], v[230:231] op_sel_hi:[1,0,0]
	v_pk_fma_f32 v[72:73], v[100:101], s[50:51], v[230:231] op_sel_hi:[1,0,0]
	v_pk_fma_f32 v[74:75], v[102:103], s[50:51], v[230:231] op_sel_hi:[1,0,0]
	v_pk_fma_f32 v[78:79], v[106:107], s[50:51], v[230:231] op_sel_hi:[1,0,0]
	v_pk_fma_f32 v[96:97], v[108:109], s[50:51], v[230:231] op_sel_hi:[1,0,0]
	v_pk_fma_f32 v[98:99], v[110:111], s[50:51], v[230:231] op_sel_hi:[1,0,0]
	v_pk_fma_f32 v[102:103], v[80:81], s[50:51], v[230:231] op_sel_hi:[1,0,0]
	v_pk_fma_f32 v[114:115], v[82:83], s[50:51], v[230:231] op_sel_hi:[1,0,0]
	v_pk_fma_f32 v[116:117], v[84:85], s[50:51], v[230:231] op_sel_hi:[1,0,0]
	v_pk_fma_f32 v[228:229], v[86:87], s[50:51], v[230:231] op_sel_hi:[1,0,0]
	v_pk_fma_f32 v[156:157], v[88:89], s[50:51], v[230:231] op_sel_hi:[1,0,0]
	v_exp_f32_e32 v113, v68
	v_exp_f32_e32 v181, v69
	v_exp_f32_e32 v183, v70
	v_exp_f32_e32 v192, v71
	v_exp_f32_e32 v193, v72
	v_exp_f32_e32 v194, v73
	v_exp_f32_e32 v195, v74
	v_exp_f32_e32 v196, v75
	v_exp_f32_e32 v197, v76
	v_exp_f32_e32 v199, v78
	v_exp_f32_e32 v216, v79
	v_exp_f32_e32 v217, v96
	v_exp_f32_e32 v218, v97
	v_exp_f32_e32 v219, v98
	v_exp_f32_e32 v220, v99
	v_pk_fma_f32 v[158:159], v[90:91], s[50:51], v[230:231] op_sel_hi:[1,0,0]
	v_pk_fma_f32 v[160:161], v[92:93], s[50:51], v[230:231] op_sel_hi:[1,0,0]
	v_pk_fma_f32 v[184:185], v[94:95], s[50:51], v[230:231] op_sel_hi:[1,0,0]
	ds_read_b128 v[98:101], v174 offset:2048
	ds_read_b128 v[104:107], v174 offset:2560
	v_exp_f32_e32 v221, v102
	v_exp_f32_e32 v222, v103
	ds_read_b64 v[102:103], v175 offset:1024
	ds_read_b64 v[108:109], v175 offset:1280
	s_waitcnt lgkmcnt(4)
	v_mfma_scale_f32_32x32x64_f8f6f4 v[66:81], v[200:205], v[120:125], 0, v162, v162 op_sel_hi:[0,0,0] cbsz:2 blgp:2
	v_exp_f32_e32 v223, v114
	v_exp_f32_e32 v224, v115
	v_exp_f32_e32 v225, v116
	v_exp_f32_e32 v226, v117
	v_mfma_scale_f32_32x32x64_f8f6f4 v[82:97], v[206:211], v[120:125], 0, v162, v162 op_sel_hi:[0,0,0] cbsz:2 blgp:2
	ds_read_b128 v[114:117], v174 offset:6144
	ds_read_b128 v[148:151], v174 offset:6656
	ds_read_b64 v[118:119], v175 offset:4096
	ds_read_b64 v[152:153], v175 offset:4352
	s_waitcnt lgkmcnt(4)
	v_mfma_scale_f32_32x32x64_f8f6f4 v[66:81], v[98:103], v[126:131], v[66:81], v162, v162 op_sel_hi:[0,0,0] cbsz:2 blgp:2
	v_exp_f32_e32 v100, v228
	v_exp_f32_e32 v101, v229
	v_exp_f32_e32 v110, v156
	v_exp_f32_e32 v111, v157
	v_exp_f32_e32 v156, v158
	v_exp_f32_e32 v157, v159
	v_mfma_scale_f32_32x32x64_f8f6f4 v[82:97], v[104:109], v[126:131], v[82:97], v162, v162 op_sel_hi:[0,0,0] cbsz:2 blgp:2
	s_waitcnt lgkmcnt(0)
	v_exp_f32_e32 v106, v160
	v_mfma_scale_f32_32x32x64_f8f6f4 v[66:81], v[114:119], v[132:137], v[66:81], v162, v162 op_sel_hi:[0,0,0] cbsz:2 blgp:2
	v_exp_f32_e32 v107, v161
	v_exp_f32_e32 v108, v184
	v_exp_f32_e32 v109, v185
	v_mfma_scale_f32_32x32x64_f8f6f4 v[82:97], v[148:153], v[132:137], v[82:97], v162, v162 op_sel_hi:[0,0,0] cbsz:2 blgp:2
	v_lshl_add_u32 v98, s12, 13, v173
	ds_read_b128 v[148:151], v98 offset:36864
	ds_read_b128 v[152:155], v98 offset:37376
	ds_read_b128 v[184:187], v98 offset:38912
	ds_read_b128 v[188:191], v98 offset:39424
	ds_read_b128 v[200:203], v98 offset:40960
	ds_read_b128 v[204:207], v98 offset:41472
	ds_read_b128 v[208:211], v98 offset:43008
	ds_read_b128 v[212:215], v98 offset:43520
	v_cvt_pk_fp8_f32 v103, v225, v226
	v_cvt_pk_fp8_f32 v98, v113, v181
	v_cvt_pk_fp8_f32 v102, v221, v222
	v_cvt_pk_fp8_f32 v99, v193, v194
	v_cvt_pk_fp8_f32 v103, v100, v101 op_sel:[0,0,1]
	v_cvt_pk_fp8_f32 v100, v197, v198
	v_cvt_pk_fp8_f32 v104, v110, v111
	v_cvt_pk_fp8_f32 v101, v217, v218
	v_cvt_pk_fp8_f32 v105, v106, v107
	v_cvt_pk_fp8_f32 v98, v183, v192 op_sel:[0,0,1]
	v_cvt_pk_fp8_f32 v102, v223, v224 op_sel:[0,0,1]
	v_cvt_pk_fp8_f32 v99, v195, v196 op_sel:[0,0,1]
	v_cvt_pk_fp8_f32 v100, v199, v216 op_sel:[0,0,1]
	v_cvt_pk_fp8_f32 v104, v156, v157 op_sel:[0,0,1]
	v_cvt_pk_fp8_f32 v101, v219, v220 op_sel:[0,0,1]
	v_cvt_pk_fp8_f32 v105, v108, v109 op_sel:[0,0,1]
	s_waitcnt lgkmcnt(0)
	s_nop 0
	v_mfma_scale_f32_32x32x64_f8f6f4 v[0:15], v[98:105], v[148:155], v[0:15], v162, v162 op_sel_hi:[0,0,0]
	s_cmpk_gt_u32 s19, 0xff
	s_cbranch_scc1 .Lmask_last
; #define SBAR() __builtin_amdgcn_sched_barrier(0)
; #define MFMA8(A, B, C) __builtin_amdgcn_mfma_scale_f32_32x32x64_f8f6f4(A, B, C, 0, 0, 0, 0x7f7f7f7f, 0, 0x7f7f7f7f)
; #define PVM(db) do { const i32x8 b = {(int)f.v[db][0][0], (int)f.v[db][0][1], (int)f.v[db][0][2], (int)f.v[db][0][3], (int)f.v[db][1][0], (int)f.v[db][1][1], (int)f.v[db][1][2], (int)f.v[db][1][3]}; \
;     o[db] = MFMA8(pa, b, o[db]); } while (0)
; DEVINL void pv_psm(f32x16* o, const VFrag& f, const i32x8& pa, f32x16& lsum, const i32x8& ones8,
;                    f32x16& p0, f32x16& p1, float& m_reg, float& mn, float& alpha, int kvalid, int hi) {
;     ...
;   float pmax = p0[0];
; #pragma unroll
;   for (int r = 1; r < 16; ++r) pmax = fmaxf(pmax, p0[r]);
;   SBAR();
;   PVM(1);
; #pragma unroll
;   for (int r = 0; r < 16; ++r) pmax = fmaxf(pmax, p1[r]);
;   { auto rr = __builtin_amdgcn_permlane32_swap(__float_as_uint(pmax), __float_as_uint(pmax), false, false);
;     pmax = fmaxf(__uint_as_float(rr[0]), __uint_as_float(rr[1])); }
;   SBAR();
;   PVM(2);
;   if (__builtin_expect(__all(pmax - m_reg <= THR / MLA_SCALE), 1)) { mn = m_reg; alpha = 1.f; }
;   else { mn = fmaxf(m_reg, pmax); alpha = __builtin_amdgcn_exp2f((m_reg - mn) * C); m_reg = mn; }
;   const float mnC = PSHIFT - mn * C;
;   const f32x2 C2 = {C, C}, M2 = {mnC, mnC};
; #pragma unroll
;   for (int r = 0; r < 16; r += 2) { f32x2 v = {p0[r], p0[r + 1]}; v = __builtin_elementwise_fma(v, C2, M2); p0[r] = v[0]; p0[r + 1] = v[1]; }
;   SBAR();
;   PVM(3);
; #pragma unroll
;   for (int r = 0; r < 16; r += 2) { f32x2 v = {p1[r], p1[r + 1]}; v = __builtin_elementwise_fma(v, C2, M2); p1[r] = v[0]; p1[r + 1] = v[1]; }
; #pragma unroll
;   for (int r = 0; r < 8; ++r) p0[r] = __builtin_amdgcn_exp2f(p0[r]);
;   SBAR();
;   lsum = MFMA8(ones8, pa, (f32x16{}));
; #pragma unroll
;   for (int r = 8; r < 16; ++r) p0[r] = __builtin_amdgcn_exp2f(p0[r]);
; DEVINL void mla_block(const Params& p, const bf16_t* __restrict__ Qn, const bf16_t* __restrict__ Qr, const char* __restrict__ K8, const char* __restrict__ Kp8,
;                       const char* __restrict__ V8, const bf16_t* __restrict__ Gb, bf16_t* __restrict__ Yb, char* lds, int pos0) {
;     ...
;     { const float alPrev = alB; pv_psm(o, vf, pa, lsum, ones8, pA0, pA1, m_reg, mnA, alA, L - (j + 1) * KVBLK, hi); LUPD(alPrev); }
;     TILE_SYNC(); RESC(alA);
.Lmask_ret:
	v_max_f32_e32 v241, v66, v67
	v_max3_f32 v241, v241, v68, v69
	v_max3_f32 v241, v241, v70, v71
	v_max3_f32 v241, v241, v72, v73
	v_max3_f32 v241, v241, v74, v75
	v_max3_f32 v241, v241, v76, v77
	v_max3_f32 v241, v241, v78, v79
	v_max3_f32 v241, v241, v80, v81
	v_mfma_scale_f32_32x32x64_f8f6f4 v[48:63], v[98:105], v[184:191], v[48:63], v162, v162 op_sel_hi:[0,0,0]
	v_max3_f32 v241, v241, v82, v83
	v_max3_f32 v241, v241, v84, v85
	v_max3_f32 v241, v241, v86, v87
	v_max3_f32 v241, v241, v88, v89
	v_max3_f32 v241, v241, v90, v91
	v_max3_f32 v241, v241, v92, v93
	v_max3_f32 v241, v241, v94, v95
	v_max3_f32 v241, v241, v96, v97
	v_mov_b32_e32 v242, v241
	s_nop 1
	v_permlane32_swap_b32_e32 v241, v242
	v_max_f32_e32 v241, v241, v242
	v_mfma_scale_f32_32x32x64_f8f6f4 v[16:31], v[98:105], v[200:207], v[16:31], v162, v162 op_sel_hi:[0,0,0]
	v_sub_f32_e32 v242, v241, v227
	v_cmp_ge_f32_e32 vcc, s69, v242
	s_cmp_eq_u64 vcc, exec
	s_cselect_b64 s[8:9], -1, 0
	v_mov_b32_e32 v198, 1.0
	v_mfma_scale_f32_32x32x64_f8f6f4 v[32:47], v[98:105], v[208:215], v[32:47], v162, v162 op_sel_hi:[0,0,0]
	s_waitcnt vmcnt(0)
	s_waitcnt vmcnt(0)
	s_barrier
	s_and_b64 vcc, exec, s[8:9]
	s_cbranch_vccnz .LBB0_576
	v_max_f32_e32 v241, v227, v241
	v_sub_f32_e32 v243, v227, v241
	v_mul_f32_e32 v243, 0x3dd53b94, v243
	v_exp_f32_e32 v198, v243
	v_mov_b32_e32 v227, v241
	v_fmamk_f32 v230, v241, 0xbdd53b94, v164
	s_and_saveexec_b64 s[16:17], s[6:7]
	ds_write_b32 v178, v198 offset:128
	s_or_b64 exec, exec, s[16:17]
	s_waitcnt lgkmcnt(0)
	v_add_u32_e32 v242, v171, v177
	ds_read_b128 v[244:247], v242 offset:224
	ds_read_b128 v[116:119], v242 offset:192
	ds_read_b128 v[148:151], v242 offset:160
	ds_read_b128 v[152:155], v242 offset:128
	s_waitcnt lgkmcnt(3)
	v_pk_mul_f32 v[12:13], v[12:13], v[244:245]
	s_waitcnt lgkmcnt(2)
	v_pk_mul_f32 v[8:9], v[8:9], v[116:117]
	s_waitcnt lgkmcnt(1)
	v_pk_mul_f32 v[4:5], v[4:5], v[148:149]
	v_pk_mul_f32 v[14:15], v[14:15], v[246:247]
	v_pk_mul_f32 v[10:11], v[10:11], v[118:119]
	v_pk_mul_f32 v[6:7], v[6:7], v[150:151]
	s_waitcnt lgkmcnt(0)
	v_pk_mul_f32 v[2:3], v[2:3], v[154:155]
	v_pk_mul_f32 v[0:1], v[0:1], v[152:153]
	v_pk_mul_f32 v[60:61], v[60:61], v[244:245]
	v_pk_mul_f32 v[56:57], v[56:57], v[116:117]
	v_pk_mul_f32 v[52:53], v[52:53], v[148:149]
	v_pk_mul_f32 v[62:63], v[62:63], v[246:247]
	v_pk_mul_f32 v[58:59], v[58:59], v[118:119]
	v_pk_mul_f32 v[54:55], v[54:55], v[150:151]
	v_pk_mul_f32 v[50:51], v[50:51], v[154:155]
	v_pk_mul_f32 v[48:49], v[48:49], v[152:153]
	v_pk_mul_f32 v[28:29], v[28:29], v[244:245]
	v_pk_mul_f32 v[24:25], v[24:25], v[116:117]
	v_pk_mul_f32 v[20:21], v[20:21], v[148:149]
	v_pk_mul_f32 v[30:31], v[30:31], v[246:247]
	v_pk_mul_f32 v[26:27], v[26:27], v[118:119]
	v_pk_mul_f32 v[22:23], v[22:23], v[150:151]
	v_pk_mul_f32 v[18:19], v[18:19], v[154:155]
	v_pk_mul_f32 v[16:17], v[16:17], v[152:153]
	v_pk_mul_f32 v[44:45], v[44:45], v[244:245]
	v_pk_mul_f32 v[40:41], v[40:41], v[116:117]
	v_pk_mul_f32 v[36:37], v[36:37], v[148:149]
	v_pk_mul_f32 v[46:47], v[46:47], v[246:247]
	v_pk_mul_f32 v[42:43], v[42:43], v[118:119]
	v_pk_mul_f32 v[38:39], v[38:39], v[150:151]
	v_pk_mul_f32 v[34:35], v[34:35], v[154:155]
	v_pk_mul_f32 v[32:33], v[32:33], v[152:153]
.LBB0_576:
	s_add_i32 s16, s53, -1
	s_and_b32 s16, s16, 3
	s_mul_i32 s16, s16, 0x2400
	v_add_u32_e32 v174, s16, v173
	v_add_u32_e32 v175, s16, v176
	ds_read_b128 v[204:207], v174
	ds_read_b64 v[208:209], v175
	ds_read_b128 v[216:219], v174 offset:512
	ds_read_b64 v[220:221], v175 offset:256
	v_pk_fma_f32 v[228:229], v[74:75], s[50:51], v[230:231] op_sel_hi:[1,0,0]
	v_pk_fma_f32 v[66:67], v[66:67], s[50:51], v[230:231] op_sel_hi:[1,0,0]
	v_pk_fma_f32 v[68:69], v[68:69], s[50:51], v[230:231] op_sel_hi:[1,0,0]
	v_pk_fma_f32 v[70:71], v[70:71], s[50:51], v[230:231] op_sel_hi:[1,0,0]
	v_pk_fma_f32 v[72:73], v[72:73], s[50:51], v[230:231] op_sel_hi:[1,0,0]
	v_pk_fma_f32 v[154:155], v[90:91], s[50:51], v[230:231] op_sel_hi:[1,0,0]
	v_pk_fma_f32 v[152:153], v[92:93], s[50:51], v[230:231] op_sel_hi:[1,0,0]
	v_pk_fma_f32 v[150:151], v[94:95], s[50:51], v[230:231] op_sel_hi:[1,0,0]
	v_pk_fma_f32 v[148:149], v[96:97], s[50:51], v[230:231] op_sel_hi:[1,0,0]
	v_exp_f32_e32 v65, v66
	v_exp_f32_e32 v197, v67
	v_exp_f32_e32 v187, v68
	v_exp_f32_e32 v189, v69
	v_exp_f32_e32 v195, v70
	v_exp_f32_e32 v196, v71
	v_exp_f32_e32 v191, v72
	v_exp_f32_e32 v192, v73
	v_fma_f32 v180, v179, v180, v240
	v_mfma_scale_f32_32x32x64_f8f6f4 v[240:255], v[232:239], v[98:105], 0, v162, v162 op_sel_hi:[0,0,0]
	v_fma_f32 v94, v76, s50, v230
	v_fma_f32 v95, v77, s50, v230
	v_fma_f32 v96, v78, s50, v230
	v_fma_f32 v97, v79, s50, v230
	v_fma_f32 v106, v80, s50, v230
	v_fma_f32 v107, v81, s50, v230
	v_exp_f32_e32 v193, v228
	v_exp_f32_e32 v194, v229
	v_exp_f32_e32 v183, v94
	v_exp_f32_e32 v184, v95
	v_exp_f32_e32 v188, v96
	v_exp_f32_e32 v190, v97
	v_exp_f32_e32 v185, v106
	v_exp_f32_e32 v186, v107
	s_add_i32 s53, s53, 2
	s_add_u32 s14, s14, 0x4000
	s_addc_u32 s15, s15, 0
	v_pk_fma_f32 v[160:161], v[82:83], s[50:51], v[230:231] op_sel_hi:[1,0,0]
	v_pk_fma_f32 v[158:159], v[84:85], s[50:51], v[230:231] op_sel_hi:[1,0,0]
	v_pk_fma_f32 v[82:83], v[86:87], s[50:51], v[230:231] op_sel_hi:[1,0,0]
	v_pk_fma_f32 v[156:157], v[88:89], s[50:51], v[230:231] op_sel_hi:[1,0,0]
	s_cmpk_gt_u32 s18, 0xfd
	v_fma_f32 v180, v182, v180, v240
	s_cbranch_scc1 .LBB0_578
	v_mov_b32_e32 v179, v198
	s_branch .LBB0_560
